# v55: grid barrier acquire invalidate issued at arrival (under the wait / the leader's L2 write-back) instead of after the release
# speedup vs baseline: 1.0186x; 1.0109x over previous
.LBB0_111:
	s_or_b64 exec, exec, s[8:9]
	v_cvt_f32_u32_e32 v5, v3
	s_waitcnt vmcnt(0)
	v_readfirstlane_b32 s6, v4
	buffer_inv sc1
	v_sub_u32_e32 v4, 0, v3
	v_rcp_iflag_f32_e32 v5, v5
	v_add_u32_e32 v6, s6, v2
	v_mul_f32_e32 v5, 0x4f7ffffe, v5
	v_cvt_u32_f32_e32 v5, v5
	v_mul_lo_u32 v2, v4, v5
	v_mul_hi_u32 v2, v5, v2
	v_add_u32_e32 v2, v5, v2
	v_mul_hi_u32 v2, v6, v2
	v_mul_lo_u32 v4, v2, v3
	v_sub_u32_e32 v4, v6, v4
	v_add_u32_e32 v5, 1, v2
	v_cmp_ge_u32_e32 vcc, v4, v3
	s_nop 1
	v_cndmask_b32_e32 v2, v2, v5, vcc
	v_sub_u32_e32 v5, v4, v3
	v_cndmask_b32_e32 v4, v4, v5, vcc
	v_add_u32_e32 v5, 1, v2
	v_cmp_ge_u32_e32 vcc, v4, v3
	v_add_u32_e32 v4, 1, v6
	s_nop 0
	v_cndmask_b32_e32 v2, v2, v5, vcc
	v_mul_lo_u32 v5, v3, v2
	v_add_u32_e32 v3, v5, v3
	v_cmp_ne_u32_e32 vcc, v4, v3
	s_and_saveexec_b64 s[6:7], vcc
	s_xor_b64 s[6:7], exec, s[6:7]
	s_cbranch_execz .LBB0_125
	s_waitcnt lgkmcnt(0)
	v_mov_b32_e32 v1, 0x2000
	global_load_dword v1, v1, s[4:5] offset:1024 sc1
	s_add_u32 s12, s4, 0x2400
	s_addc_u32 s13, s5, 0
	s_waitcnt vmcnt(0)
	v_cmp_eq_u32_e32 vcc, v1, v2
	s_and_saveexec_b64 s[8:9], vcc
	s_cbranch_execz .LBB0_124
	s_add_u32 s10, s82, 0x4200
	s_addc_u32 s11, s83, 0
	s_mov_b32 s24, 1
	s_mov_b64 s[14:15], 0
	v_mov_b32_e32 v1, 0
	s_branch .LBB0_115

.LBB0_124:
	s_or_b64 exec, exec, s[8:9]
	s_waitcnt vmcnt(0)
	s_waitcnt vmcnt(0)

.LBB0_142:
	s_or_b64 exec, exec, s[6:7]
	s_mov_b64 s[6:7], exec
	v_mbcnt_lo_u32_b32 v1, s6, 0
	v_mbcnt_hi_u32_b32 v1, s7, v1
	v_cmp_eq_u32_e32 vcc, 0, v1
	s_waitcnt vmcnt(0)
	s_and_saveexec_b64 s[8:9], vcc
	s_cbranch_execz .LBB0_144
	s_bcnt1_i32_b64 s6, s[6:7]
	v_mov_b32_e32 v1, 0x2000
	v_mov_b32_e32 v2, s6
	global_atomic_add v1, v2, s[4:5] offset:1024
.LBB0_144:
	s_or_b64 exec, exec, s[8:9]
	s_waitcnt vmcnt(0)

.LBB0_594:
	s_or_b64 exec, exec, s[6:7]
	v_cvt_f32_u32_e32 v5, v3
	s_waitcnt vmcnt(0)
	v_readfirstlane_b32 s4, v4
	buffer_inv sc1
	v_sub_u32_e32 v4, 0, v3
	v_rcp_iflag_f32_e32 v5, v5
	v_add_u32_e32 v6, s4, v2
	v_mul_f32_e32 v5, 0x4f7ffffe, v5
	v_cvt_u32_f32_e32 v5, v5
	v_mul_lo_u32 v2, v4, v5
	v_mul_hi_u32 v2, v5, v2
	v_add_u32_e32 v2, v5, v2
	v_mul_hi_u32 v2, v6, v2
	v_mul_lo_u32 v4, v2, v3
	v_sub_u32_e32 v4, v6, v4
	v_add_u32_e32 v5, 1, v2
	v_cmp_ge_u32_e32 vcc, v4, v3
	s_nop 1
	v_cndmask_b32_e32 v2, v2, v5, vcc
	v_sub_u32_e32 v5, v4, v3
	v_cndmask_b32_e32 v4, v4, v5, vcc
	v_add_u32_e32 v5, 1, v2
	v_cmp_ge_u32_e32 vcc, v4, v3
	v_add_u32_e32 v4, 1, v6
	s_nop 0
	v_cndmask_b32_e32 v2, v2, v5, vcc
	v_mul_lo_u32 v5, v3, v2
	v_add_u32_e32 v3, v5, v3
	v_cmp_ne_u32_e32 vcc, v4, v3
	s_and_saveexec_b64 s[4:5], vcc
	s_xor_b64 s[4:5], exec, s[4:5]
	s_cbranch_execz .LBB0_608
	s_waitcnt lgkmcnt(0)
	v_mov_b32_e32 v1, 0x2000
	global_load_dword v1, v1, s[2:3] offset:1024 sc1
	s_add_u32 s10, s2, 0x2400
	s_addc_u32 s11, s3, 0
	s_waitcnt vmcnt(0)
	v_cmp_eq_u32_e32 vcc, v1, v2
	s_and_saveexec_b64 s[6:7], vcc
	s_cbranch_execz .LBB0_607
	s_add_u32 s8, s82, 0x4200
	s_addc_u32 s9, s83, 0
	s_mov_b32 s24, 1
	s_mov_b64 s[12:13], 0
	v_mov_b32_e32 v1, 0
	s_branch .LBB0_598

.LBB0_607:
	s_or_b64 exec, exec, s[6:7]
	s_waitcnt vmcnt(0)
	s_waitcnt vmcnt(0)

.LBB0_625:
	s_or_b64 exec, exec, s[4:5]
	s_mov_b64 s[4:5], exec
	v_mbcnt_lo_u32_b32 v1, s4, 0
	v_mbcnt_hi_u32_b32 v1, s5, v1
	v_cmp_eq_u32_e32 vcc, 0, v1
	s_waitcnt vmcnt(0)
	s_and_saveexec_b64 s[6:7], vcc
	s_cbranch_execz .LBB0_627
	s_bcnt1_i32_b64 s4, s[4:5]
	v_mov_b32_e32 v1, 0x2000
	v_mov_b32_e32 v2, s4
	global_atomic_add v1, v2, s[2:3] offset:1024
.LBB0_627:
	s_or_b64 exec, exec, s[6:7]
	s_waitcnt vmcnt(0)

.LBB0_730:
	s_or_b64 exec, exec, s[4:5]
	s_mov_b64 s[4:5], exec
	v_mbcnt_lo_u32_b32 v1, s4, 0
	v_mbcnt_hi_u32_b32 v1, s5, v1
	v_cmp_eq_u32_e32 vcc, 0, v1
	s_waitcnt vmcnt(0)
	s_and_saveexec_b64 s[6:7], vcc
	s_cbranch_execz .LBB0_732
	s_bcnt1_i32_b64 s4, s[4:5]
	v_mov_b32_e32 v1, 0x2000
	v_mov_b32_e32 v2, s4
	global_atomic_add v1, v2, s[2:3] offset:1024
.LBB0_732:
	s_or_b64 exec, exec, s[6:7]
	s_waitcnt vmcnt(0)

.LBB0_1197:
	s_or_b64 exec, exec, s[4:5]
	s_mov_b64 s[4:5], exec
	v_mbcnt_lo_u32_b32 v1, s4, 0
	v_mbcnt_hi_u32_b32 v1, s5, v1
	v_cmp_eq_u32_e32 vcc, 0, v1
	s_waitcnt vmcnt(0)
	s_and_saveexec_b64 s[6:7], vcc
	s_cbranch_execz .LBB0_1199
	s_bcnt1_i32_b64 s4, s[4:5]
	v_mov_b32_e32 v1, 0x2000
	v_mov_b32_e32 v2, s4
	global_atomic_add v1, v2, s[2:3] offset:1024
.LBB0_1199:
	s_or_b64 exec, exec, s[6:7]
	s_waitcnt vmcnt(0)

.LBB0_1231:
	s_or_b64 exec, exec, s[6:7]
	v_cvt_f32_u32_e32 v5, v3
	s_waitcnt vmcnt(0)
	v_readfirstlane_b32 s4, v4
	buffer_inv sc1
	v_sub_u32_e32 v4, 0, v3
	v_rcp_iflag_f32_e32 v5, v5
	v_add_u32_e32 v6, s4, v2
	v_mul_f32_e32 v5, 0x4f7ffffe, v5
	v_cvt_u32_f32_e32 v5, v5
	v_mul_lo_u32 v2, v4, v5
	v_mul_hi_u32 v2, v5, v2
	v_add_u32_e32 v2, v5, v2
	v_mul_hi_u32 v2, v6, v2
	v_mul_lo_u32 v4, v2, v3
	v_sub_u32_e32 v4, v6, v4
	v_add_u32_e32 v5, 1, v2
	v_cmp_ge_u32_e32 vcc, v4, v3
	s_nop 1
	v_cndmask_b32_e32 v2, v2, v5, vcc
	v_sub_u32_e32 v5, v4, v3
	v_cndmask_b32_e32 v4, v4, v5, vcc
	v_add_u32_e32 v5, 1, v2
	v_cmp_ge_u32_e32 vcc, v4, v3
	v_add_u32_e32 v4, 1, v6
	s_nop 0
	v_cndmask_b32_e32 v2, v2, v5, vcc
	v_mul_lo_u32 v5, v3, v2
	v_add_u32_e32 v3, v5, v3
	v_cmp_ne_u32_e32 vcc, v4, v3
	s_and_saveexec_b64 s[4:5], vcc
	s_xor_b64 s[4:5], exec, s[4:5]
	s_cbranch_execz .LBB0_1245
	s_waitcnt lgkmcnt(0)
	v_mov_b32_e32 v1, 0x2000
	global_load_dword v1, v1, s[2:3] offset:1024 sc1
	s_add_u32 s10, s2, 0x2400
	s_addc_u32 s11, s3, 0
	s_waitcnt vmcnt(0)
	v_cmp_eq_u32_e32 vcc, v1, v2
	s_and_saveexec_b64 s[6:7], vcc
	s_cbranch_execz .LBB0_1244
	s_add_u32 s8, s82, 0x4200
	s_addc_u32 s9, s83, 0
	s_mov_b32 s22, 1
	s_mov_b64 s[12:13], 0
	v_mov_b32_e32 v1, 0
	s_branch .LBB0_1235

.LBB0_1262:
	s_or_b64 exec, exec, s[4:5]
	s_mov_b64 s[4:5], exec
	v_mbcnt_lo_u32_b32 v1, s4, 0
	v_mbcnt_hi_u32_b32 v1, s5, v1
	v_cmp_eq_u32_e32 vcc, 0, v1
	s_waitcnt vmcnt(0)
	s_and_saveexec_b64 s[6:7], vcc
	s_cbranch_execz .LBB0_1264
	s_bcnt1_i32_b64 s4, s[4:5]
	v_mov_b32_e32 v1, 0x2000
	v_mov_b32_e32 v2, s4
	global_atomic_add v1, v2, s[2:3] offset:1024
.LBB0_1264:
	s_or_b64 exec, exec, s[6:7]
	s_waitcnt vmcnt(0)

.LBB0_1491:
	s_or_b64 exec, exec, s[4:5]
	s_mov_b64 s[4:5], exec
	v_mbcnt_lo_u32_b32 v1, s4, 0
	v_mbcnt_hi_u32_b32 v1, s5, v1
	v_cmp_eq_u32_e32 vcc, 0, v1
	s_waitcnt vmcnt(0)
	s_and_saveexec_b64 s[6:7], vcc
	s_cbranch_execz .LBB0_1493
	s_bcnt1_i32_b64 s4, s[4:5]
	v_mov_b32_e32 v1, 0x2000
	v_mov_b32_e32 v2, s4
	global_atomic_add v1, v2, s[2:3] offset:1024
.LBB0_1493:
	s_or_b64 exec, exec, s[6:7]
	s_waitcnt vmcnt(0)

.LBB0_1571:
	s_or_b64 exec, exec, s[8:9]
	v_cvt_f32_u32_e32 v5, v3
	s_waitcnt vmcnt(0)
	v_readfirstlane_b32 s6, v4
	buffer_inv sc1
	v_sub_u32_e32 v4, 0, v3
	v_rcp_iflag_f32_e32 v5, v5
	v_add_u32_e32 v6, s6, v2
	v_mul_f32_e32 v5, 0x4f7ffffe, v5
	v_cvt_u32_f32_e32 v5, v5
	v_mul_lo_u32 v2, v4, v5
	v_mul_hi_u32 v2, v5, v2
	v_add_u32_e32 v2, v5, v2
	v_mul_hi_u32 v2, v6, v2
	v_mul_lo_u32 v4, v2, v3
	v_sub_u32_e32 v4, v6, v4
	v_add_u32_e32 v5, 1, v2
	v_cmp_ge_u32_e32 vcc, v4, v3
	s_nop 1
	v_cndmask_b32_e32 v2, v2, v5, vcc
	v_sub_u32_e32 v5, v4, v3
	v_cndmask_b32_e32 v4, v4, v5, vcc
	v_add_u32_e32 v5, 1, v2
	v_cmp_ge_u32_e32 vcc, v4, v3
	v_add_u32_e32 v4, 1, v6
	s_nop 0
	v_cndmask_b32_e32 v2, v2, v5, vcc
	v_mul_lo_u32 v5, v3, v2
	v_add_u32_e32 v3, v5, v3
	v_cmp_ne_u32_e32 vcc, v4, v3
	s_and_saveexec_b64 s[6:7], vcc
	s_xor_b64 s[6:7], exec, s[6:7]
	s_cbranch_execz .LBB0_1585
	s_waitcnt lgkmcnt(0)
	v_mov_b32_e32 v1, 0x2000
	global_load_dword v1, v1, s[2:3] offset:1024 sc1
	s_add_u32 s12, s2, 0x2400
	s_addc_u32 s13, s3, 0
	s_waitcnt vmcnt(0)
	v_cmp_eq_u32_e32 vcc, v1, v2
	s_and_saveexec_b64 s[8:9], vcc
	s_cbranch_execz .LBB0_1584
	s_add_u32 s10, s82, 0x4200
	s_addc_u32 s11, s83, 0
	s_mov_b32 s24, 1
	s_mov_b64 s[14:15], 0
	v_mov_b32_e32 v1, 0
	s_branch .LBB0_1575

.LBB0_1602:
	s_or_b64 exec, exec, s[6:7]
	s_mov_b64 s[6:7], exec
	v_mbcnt_lo_u32_b32 v1, s6, 0
	v_mbcnt_hi_u32_b32 v1, s7, v1
	v_cmp_eq_u32_e32 vcc, 0, v1
	s_waitcnt vmcnt(0)
	s_and_saveexec_b64 s[8:9], vcc
	s_cbranch_execz .LBB0_1604
	s_bcnt1_i32_b64 s6, s[6:7]
	v_mov_b32_e32 v1, 0x2000
	v_mov_b32_e32 v2, s6
	global_atomic_add v1, v2, s[2:3] offset:1024
.LBB0_1604:
	s_or_b64 exec, exec, s[8:9]
	s_waitcnt vmcnt(0)

.LBB0_1692:
	s_or_b64 exec, exec, s[4:5]
	s_mov_b64 s[4:5], exec
	v_mbcnt_lo_u32_b32 v1, s4, 0
	v_mbcnt_hi_u32_b32 v1, s5, v1
	v_cmp_eq_u32_e32 vcc, 0, v1
	s_waitcnt vmcnt(0)
	s_and_saveexec_b64 s[6:7], vcc
	s_cbranch_execz .LBB0_1694
	s_bcnt1_i32_b64 s4, s[4:5]
	v_mov_b32_e32 v1, 0x2000
	v_mov_b32_e32 v2, s4
	global_atomic_add v1, v2, s[2:3] offset:1024
.LBB0_1694:
	s_or_b64 exec, exec, s[6:7]
	s_waitcnt vmcnt(0)

.LBB0_1789:
	s_or_b64 exec, exec, s[4:5]
	s_mov_b64 s[4:5], exec
	v_mbcnt_lo_u32_b32 v1, s4, 0
	v_mbcnt_hi_u32_b32 v1, s5, v1
	v_cmp_eq_u32_e32 vcc, 0, v1
	s_waitcnt vmcnt(0)
	s_and_saveexec_b64 s[6:7], vcc
	s_cbranch_execz .LBB0_1791
	s_bcnt1_i32_b64 s4, s[4:5]
	v_mov_b32_e32 v1, 0x2000
	v_mov_b32_e32 v2, s4
	global_atomic_add v1, v2, s[2:3] offset:1024
.LBB0_1791:
	s_or_b64 exec, exec, s[6:7]
	s_waitcnt vmcnt(0)

.LBB0_1855:
	s_or_b64 exec, exec, s[6:7]
	v_cvt_f32_u32_e32 v5, v3
	s_waitcnt vmcnt(0)
	v_readfirstlane_b32 s4, v4
	buffer_inv sc1
	v_sub_u32_e32 v4, 0, v3
	v_rcp_iflag_f32_e32 v5, v5
	v_add_u32_e32 v6, s4, v2
	v_mul_f32_e32 v5, 0x4f7ffffe, v5
	v_cvt_u32_f32_e32 v5, v5
	v_mul_lo_u32 v2, v4, v5
	v_mul_hi_u32 v2, v5, v2
	v_add_u32_e32 v2, v5, v2
	v_mul_hi_u32 v2, v6, v2
	v_mul_lo_u32 v4, v2, v3
	v_sub_u32_e32 v4, v6, v4
	v_add_u32_e32 v5, 1, v2
	v_cmp_ge_u32_e32 vcc, v4, v3
	s_nop 1
	v_cndmask_b32_e32 v2, v2, v5, vcc
	v_sub_u32_e32 v5, v4, v3
	v_cndmask_b32_e32 v4, v4, v5, vcc
	v_add_u32_e32 v5, 1, v2
	v_cmp_ge_u32_e32 vcc, v4, v3
	v_add_u32_e32 v4, 1, v6
	s_nop 0
	v_cndmask_b32_e32 v2, v2, v5, vcc
	v_mul_lo_u32 v5, v3, v2
	v_add_u32_e32 v3, v5, v3
	v_cmp_ne_u32_e32 vcc, v4, v3
	s_and_saveexec_b64 s[4:5], vcc
	s_xor_b64 s[4:5], exec, s[4:5]
	s_cbranch_execz .LBB0_1869
	s_waitcnt lgkmcnt(0)
	v_mov_b32_e32 v1, 0x2000
	global_load_dword v1, v1, s[2:3] offset:1024 sc1
	s_add_u32 s12, s2, 0x2400
	s_addc_u32 s13, s3, 0
	s_waitcnt vmcnt(0)
	v_cmp_eq_u32_e32 vcc, v1, v2
	s_and_saveexec_b64 s[6:7], vcc
	s_cbranch_execz .LBB0_1868
	s_add_u32 s8, s82, 0x4200
	s_addc_u32 s9, s83, 0
	s_mov_b32 s24, 1
	s_mov_b64 s[14:15], 0
	v_mov_b32_e32 v1, 0
	s_branch .LBB0_1859

.LBB0_1886:
	s_or_b64 exec, exec, s[4:5]
	s_mov_b64 s[4:5], exec
	v_mbcnt_lo_u32_b32 v1, s4, 0
	v_mbcnt_hi_u32_b32 v1, s5, v1
	v_cmp_eq_u32_e32 vcc, 0, v1
	s_waitcnt vmcnt(0)
	s_and_saveexec_b64 s[6:7], vcc
	s_cbranch_execz .LBB0_1888
	s_bcnt1_i32_b64 s4, s[4:5]
	v_mov_b32_e32 v1, 0x2000
	v_mov_b32_e32 v2, s4
	global_atomic_add v1, v2, s[2:3] offset:1024
.LBB0_1888:
	s_or_b64 exec, exec, s[6:7]
	s_waitcnt vmcnt(0)
